# attention tile loop: wave priority 0 during the pure-VALU map-0 softmax, priority 1 during the MFMA-carrying phases
# speedup vs baseline: 1.0036x; 1.0018x over previous
; #define LAS __attribute__((address_space(3)))
; __device__ __forceinline__ void dattn_unit(LAS unsigned char* lds, int b, int h, int qb, const bf16* Q, const bf16* K, const bf16* V, bf16* YB, float lam, const float* subg, float oml, int tid) {
;     ...
;             for (int cb = 0; cb < 4; ++cb) { const LAS bf16* vp = Vt + (32 * cb + ql) * 72 + 32 * sub + 4 * hi;
;                 const v2u a0 = *(const LAS v2u*)(vp), a1 = *(const LAS v2u*)(vp + 8), a2 = *(const LAS v2u*)(vp + 16), a3 = *(const LAS v2u*)(vp + 24);
;                 const v4u f0 = {a0.x, a0.y, a1.x, a1.y}, f1 = {a2.x, a2.y, a3.x, a3.y};
;                 o[0][cb] = __builtin_amdgcn_mfma_f32_32x32x16_bf16(__builtin_bit_cast(bf16x8, f0), pA0, o[0][cb], 0, 0, 0);
;                 o[1][cb] = __builtin_amdgcn_mfma_f32_32x32x16_bf16(__builtin_bit_cast(bf16x8, f0), pA1, o[1][cb], 0, 0, 0);
;                 o[0][cb] = __builtin_amdgcn_mfma_f32_32x32x16_bf16(__builtin_bit_cast(bf16x8, f1), pB0, o[0][cb], 0, 0, 0);
;                 o[1][cb] = __builtin_amdgcn_mfma_f32_32x32x16_bf16(__builtin_bit_cast(bf16x8, f1), pB1, o[1][cb], 0, 0, 0); }
.Lsm0_0:
	s_setprio 0
	v_exp_f32_e32 v201, v144
	v_exp_f32_e32 v202, v145
	v_exp_f32_e32 v203, v146
	v_exp_f32_e32 v204, v147
	v_exp_f32_e32 v205, v148
	v_add_f32_e32 v144, v202, v201
	v_exp_f32_e32 v206, v149
	v_add_f32_e32 v144, v203, v144
	v_exp_f32_e32 v207, v150
	v_add_f32_e32 v144, v204, v144
	v_exp_f32_e32 v218, v151
	v_add_f32_e32 v144, v205, v144
	v_exp_f32_e32 v147, v152
	v_add_f32_e32 v144, v206, v144
	v_exp_f32_e32 v148, v153
	v_add_f32_e32 v144, v207, v144
	v_exp_f32_e32 v149, v154
	v_add_f32_e32 v144, v218, v144
	v_exp_f32_e32 v150, v155
	v_add_f32_e32 v144, v147, v144
	v_exp_f32_e32 v151, v156
	v_add_f32_e32 v144, v148, v144
	v_exp_f32_e32 v152, v157
	v_add_f32_e32 v144, v149, v144
	v_exp_f32_e32 v153, v158
	v_add_f32_e32 v144, v150, v144
	v_exp_f32_e32 v154, v159
	v_add_f32_e32 v144, v151, v144
	v_add_f32_e32 v144, v152, v144
	v_add_f32_e32 v144, v153, v144
	v_add_f32_e32 v145, v154, v144
	v_cmp_lt_f32_e32 vcc, s82, v145
	s_cmp_lg_u64 vcc, 0
	s_cselect_b64 s[48:49], -1, 0
	s_cbranch_vccz .LBB0_232
	v_max_f32_e32 v146, v204, v204
	v_max_f32_e32 v155, v203, v203
	v_max_f32_e32 v146, v155, v146
	v_max_f32_e32 v155, v218, v218
	v_max_f32_e32 v156, v207, v207
	v_max_f32_e32 v155, v156, v155
	v_max_f32_e32 v156, v148, v148
	v_max_f32_e32 v157, v147, v147
	v_max_f32_e32 v156, v157, v156
	v_max_f32_e32 v157, v150, v150
	v_max_f32_e32 v158, v149, v149
	v_max_f32_e32 v157, v158, v157
	v_max_f32_e32 v158, v154, v154
	v_max_f32_e32 v159, v153, v153
	v_max_f32_e32 v158, v159, v158
	v_max3_f32 v158, v151, v152, v158
	v_max3_f32 v146, v201, v202, v146
	v_max3_f32 v155, v205, v206, v155
	v_max3_f32 v156, v156, v157, v158
	v_max3_f32 v146, v146, v155, v156
	v_mov_b32_e32 v155, v146
	s_nop 1
	v_permlane32_swap_b32_e32 v146, v155
	v_max_f32_e32 v155, v155, v155
	v_max_f32_e32 v146, v146, v146
	v_max_f32_e32 v146, v146, v155
.LBB0_232:
	v_cvt_pk_bf16_f32 v224, v201, v202
	v_cvt_pk_bf16_f32 v225, v203, v204
	v_cvt_pk_bf16_f32 v226, v205, v206
	v_cvt_pk_bf16_f32 v227, v207, v218
	v_cvt_pk_bf16_f32 v148, v147, v148
	v_cvt_pk_bf16_f32 v149, v149, v150
	v_cvt_pk_bf16_f32 v150, v151, v152
	v_cvt_pk_bf16_f32 v151, v153, v154
	ds_read_b128 v[204:207], v219 offset:18464
	ds_read_b128 v[200:203], v219 offset:32288
	v_add_f32_e32 v179, v179, v145
	v_exp_f32_e32 v155, v128
	v_exp_f32_e32 v129, v129
	v_exp_f32_e32 v130, v130
	v_exp_f32_e32 v131, v131
	s_setprio 1
	s_waitcnt lgkmcnt(2)
	v_mfma_f32_32x32x16_bf16 v[80:95], v[228:231], v[224:227], v[80:95]
	v_exp_f32_e32 v132, v132
	v_add_f32_e32 v128, v129, v155
	v_exp_f32_e32 v156, v133
	v_mfma_f32_32x32x16_bf16 v[80:95], v[232:235], v[148:151], v[80:95]
	v_add_f32_e32 v128, v130, v128
	v_exp_f32_e32 v157, v134
	v_add_f32_e32 v128, v131, v128
	v_exp_f32_e32 v158, v135
	v_mfma_f32_32x32x16_bf16 v[48:63], v[236:239], v[224:227], v[48:63]
	v_add_f32_e32 v128, v132, v128
	v_exp_f32_e32 v133, v136
	v_add_f32_e32 v128, v156, v128
	v_exp_f32_e32 v134, v137
	v_mfma_f32_32x32x16_bf16 v[48:63], v[240:243], v[148:151], v[48:63]
	v_add_f32_e32 v128, v157, v128
	v_exp_f32_e32 v135, v138
	v_add_f32_e32 v128, v158, v128
	v_exp_f32_e32 v136, v139
	v_mfma_f32_32x32x16_bf16 v[16:31], v[212:215], v[224:227], v[16:31]
	v_add_f32_e32 v128, v133, v128
	v_exp_f32_e32 v137, v140
	v_add_f32_e32 v128, v134, v128
	v_exp_f32_e32 v138, v141
	v_mfma_f32_32x32x16_bf16 v[112:127], v[220:223], v[224:227], v[112:127]
	v_add_f32_e32 v128, v135, v128
	v_exp_f32_e32 v139, v142
	v_add_f32_e32 v128, v136, v128
	v_exp_f32_e32 v140, v143
	s_waitcnt lgkmcnt(1)
	v_mfma_f32_32x32x16_bf16 v[112:127], v[204:207], v[148:151], v[112:127]
	v_add_f32_e32 v128, v137, v128
	v_add_f32_e32 v128, v138, v128
	v_add_f32_e32 v128, v139, v128
	v_add_f32_e32 v128, v140, v128
	s_waitcnt lgkmcnt(0)
	v_mfma_f32_32x32x16_bf16 v[16:31], v[200:203], v[148:151], v[16:31]
	v_cmp_lt_f32_e32 vcc, s82, v128
	s_cmp_lg_u64 vcc, 0
	s_cselect_b64 s[46:47], -1, 0
	s_cbranch_vccz .LBB0_234
	v_max_f32_e32 v141, v131, v131
	v_max_f32_e32 v142, v130, v130
	v_max_f32_e32 v141, v142, v141
	v_max_f32_e32 v142, v158, v158
	v_max_f32_e32 v143, v157, v157
	v_max_f32_e32 v142, v143, v142
	v_max_f32_e32 v143, v134, v134
	v_max_f32_e32 v144, v133, v133
	v_max_f32_e32 v143, v144, v143
	v_max_f32_e32 v144, v136, v136
	v_max_f32_e32 v159, v135, v135
	v_max_f32_e32 v144, v159, v144
	v_max_f32_e32 v159, v140, v140
	v_max_f32_e32 v147, v139, v139
	v_max_f32_e32 v159, v147, v159
	v_max3_f32 v159, v137, v138, v159
	v_max3_f32 v141, v155, v129, v141
	v_max3_f32 v142, v132, v156, v142
	v_max3_f32 v143, v143, v144, v159
	v_max3_f32 v141, v141, v142, v143
	v_mov_b32_e32 v142, v141
	s_nop 1
	v_permlane32_swap_b32_e32 v141, v142
	v_max_f32_e32 v142, v142, v142
	v_max_f32_e32 v141, v141, v141
	v_max_f32_e32 v144, v141, v142

; #define LAS __attribute__((address_space(3)))
; __device__ __forceinline__ void dattn_unit(LAS unsigned char* lds, int b, int h, int qb, const bf16* Q, const bf16* K, const bf16* V, bf16* YB, float lam, const float* subg, float oml, int tid) {
;     ...
;             for (int cb = 0; cb < 4; ++cb) { const LAS bf16* vp = Vt + (32 * cb + ql) * 72 + 32 * sub + 4 * hi;
;                 const v2u a0 = *(const LAS v2u*)(vp), a1 = *(const LAS v2u*)(vp + 8), a2 = *(const LAS v2u*)(vp + 16), a3 = *(const LAS v2u*)(vp + 24);
;                 const v4u f0 = {a0.x, a0.y, a1.x, a1.y}, f1 = {a2.x, a2.y, a3.x, a3.y};
;                 o[0][cb] = __builtin_amdgcn_mfma_f32_32x32x16_bf16(__builtin_bit_cast(bf16x8, f0), pA0, o[0][cb], 0, 0, 0);
;                 o[1][cb] = __builtin_amdgcn_mfma_f32_32x32x16_bf16(__builtin_bit_cast(bf16x8, f0), pA1, o[1][cb], 0, 0, 0);
;                 o[0][cb] = __builtin_amdgcn_mfma_f32_32x32x16_bf16(__builtin_bit_cast(bf16x8, f1), pB0, o[0][cb], 0, 0, 0);
;                 o[1][cb] = __builtin_amdgcn_mfma_f32_32x32x16_bf16(__builtin_bit_cast(bf16x8, f1), pB1, o[1][cb], 0, 0, 0); }
.Lsm0_1:
	s_setprio 0
	v_exp_f32_e32 v199, v144
	v_exp_f32_e32 v204, v145
	v_exp_f32_e32 v205, v146
	v_exp_f32_e32 v206, v147
	v_exp_f32_e32 v207, v148
	v_add_f32_e32 v144, v204, v199
	v_exp_f32_e32 v218, v149
	v_add_f32_e32 v144, v205, v144
	v_exp_f32_e32 v219, v150
	v_add_f32_e32 v144, v206, v144
	v_exp_f32_e32 v220, v151
	v_add_f32_e32 v144, v207, v144
	v_exp_f32_e32 v147, v152
	v_add_f32_e32 v144, v218, v144
	v_exp_f32_e32 v148, v153
	v_add_f32_e32 v144, v219, v144
	v_exp_f32_e32 v149, v154
	v_add_f32_e32 v144, v220, v144
	v_exp_f32_e32 v150, v155
	v_add_f32_e32 v144, v147, v144
	v_exp_f32_e32 v151, v156
	v_add_f32_e32 v144, v148, v144
	v_exp_f32_e32 v152, v157
	v_add_f32_e32 v144, v149, v144
	v_exp_f32_e32 v153, v158
	v_add_f32_e32 v144, v150, v144
	v_exp_f32_e32 v154, v159
	v_add_f32_e32 v144, v151, v144
	v_add_f32_e32 v144, v152, v144
	v_add_f32_e32 v144, v153, v144
	v_add_f32_e32 v145, v154, v144
	v_cmp_lt_f32_e32 vcc, s82, v145
	s_cmp_lg_u64 vcc, 0
	s_cselect_b64 s[48:49], -1, 0
	s_cbranch_vccz .LBB0_243
	v_max_f32_e32 v146, v206, v206
	v_max_f32_e32 v155, v205, v205
	v_max_f32_e32 v146, v155, v146
	v_max_f32_e32 v155, v220, v220
	v_max_f32_e32 v156, v219, v219
	v_max_f32_e32 v155, v156, v155
	v_max_f32_e32 v156, v148, v148
	v_max_f32_e32 v157, v147, v147
	v_max_f32_e32 v156, v157, v156
	v_max_f32_e32 v157, v150, v150
	v_max_f32_e32 v158, v149, v149
	v_max_f32_e32 v157, v158, v157
	v_max_f32_e32 v158, v154, v154
	v_max_f32_e32 v159, v153, v153
	v_max_f32_e32 v158, v159, v158
	v_max3_f32 v158, v151, v152, v158
	v_max3_f32 v146, v199, v204, v146
	v_max3_f32 v155, v207, v218, v155
	v_max3_f32 v156, v156, v157, v158
	v_max3_f32 v146, v146, v155, v156
	v_mov_b32_e32 v155, v146
	s_nop 1
	v_permlane32_swap_b32_e32 v146, v155
	v_max_f32_e32 v155, v155, v155
	v_max_f32_e32 v146, v146, v146
	v_max_f32_e32 v146, v146, v155
.LBB0_243:
	v_cvt_pk_bf16_f32 v205, v205, v206
	v_cvt_pk_bf16_f32 v206, v207, v218
	v_cvt_pk_bf16_f32 v207, v219, v220
	v_cvt_pk_bf16_f32 v204, v199, v204
	v_cvt_pk_bf16_f32 v148, v147, v148
	v_cvt_pk_bf16_f32 v149, v149, v150
	v_cvt_pk_bf16_f32 v150, v151, v152
	v_cvt_pk_bf16_f32 v151, v153, v154
	ds_read_b128 v[218:221], v243 offset:32352
	v_add_f32_e32 v179, v179, v145
	v_exp_f32_e32 v155, v128
	v_exp_f32_e32 v129, v129
	v_exp_f32_e32 v130, v130
	v_exp_f32_e32 v131, v131
	s_setprio 1
	s_waitcnt lgkmcnt(1)
	v_mfma_f32_32x32x16_bf16 v[80:95], v[222:225], v[204:207], v[80:95]
	v_exp_f32_e32 v132, v132
	v_add_f32_e32 v128, v129, v155
	v_exp_f32_e32 v156, v133
	v_mfma_f32_32x32x16_bf16 v[80:95], v[226:229], v[148:151], v[80:95]
	v_add_f32_e32 v128, v130, v128
	v_exp_f32_e32 v157, v134
	v_add_f32_e32 v128, v131, v128
	v_exp_f32_e32 v158, v135
	v_mfma_f32_32x32x16_bf16 v[48:63], v[230:233], v[204:207], v[48:63]
	v_add_f32_e32 v128, v132, v128
	v_exp_f32_e32 v133, v136
	v_add_f32_e32 v128, v156, v128
	v_exp_f32_e32 v134, v137
	v_mfma_f32_32x32x16_bf16 v[48:63], v[234:237], v[148:151], v[48:63]
	v_add_f32_e32 v128, v157, v128
	v_exp_f32_e32 v135, v138
	v_add_f32_e32 v128, v158, v128
	v_exp_f32_e32 v136, v139
	v_mfma_f32_32x32x16_bf16 v[16:31], v[238:241], v[204:207], v[16:31]
	v_add_f32_e32 v128, v133, v128
	v_exp_f32_e32 v137, v140
	v_add_f32_e32 v128, v134, v128
	v_exp_f32_e32 v138, v141
	v_mfma_f32_32x32x16_bf16 v[112:127], v[212:215], v[204:207], v[112:127]
	v_add_f32_e32 v128, v135, v128
	v_exp_f32_e32 v139, v142
	v_add_f32_e32 v128, v136, v128
	v_exp_f32_e32 v140, v143
	v_mfma_f32_32x32x16_bf16 v[112:127], v[200:203], v[148:151], v[112:127]
	v_add_f32_e32 v128, v137, v128
	v_add_f32_e32 v128, v138, v128
	v_add_f32_e32 v128, v139, v128
	v_add_f32_e32 v128, v140, v128
	s_waitcnt lgkmcnt(0)
	v_mfma_f32_32x32x16_bf16 v[16:31], v[218:221], v[148:151], v[16:31]
	v_cmp_lt_f32_e32 vcc, s82, v128
	s_cmp_lg_u64 vcc, 0
	s_cselect_b64 s[46:47], -1, 0
	s_cbranch_vccz .LBB0_245
	v_max_f32_e32 v141, v131, v131
	v_max_f32_e32 v142, v130, v130
	v_max_f32_e32 v141, v142, v141
	v_max_f32_e32 v142, v158, v158
	v_max_f32_e32 v143, v157, v157
	v_max_f32_e32 v142, v143, v142
	v_max_f32_e32 v143, v134, v134
	v_max_f32_e32 v144, v133, v133
	v_max_f32_e32 v143, v144, v143
	v_max_f32_e32 v144, v136, v136
	v_max_f32_e32 v159, v135, v135
	v_max_f32_e32 v144, v159, v144
	v_max_f32_e32 v159, v140, v140
	v_max_f32_e32 v147, v139, v139
	v_max_f32_e32 v159, v147, v159
	v_max3_f32 v159, v137, v138, v159
	v_max3_f32 v141, v155, v129, v141
	v_max3_f32 v142, v132, v156, v142
	v_max3_f32 v143, v143, v144, v159
	v_max3_f32 v141, v141, v142, v143
	v_mov_b32_e32 v142, v141
	s_nop 1
	v_permlane32_swap_b32_e32 v141, v142
	v_max_f32_e32 v142, v142, v142
	v_max_f32_e32 v141, v141, v141
	v_max_f32_e32 v144, v141, v142

; #define LAS __attribute__((address_space(3)))
; __device__ __forceinline__ void dattn_unit(LAS unsigned char* lds, int b, int h, int qb, const bf16* Q, const bf16* K, const bf16* V, bf16* YB, float lam, const float* subg, float oml, int tid) {
;     ...
;             if (kvbase + 32 * sub > qmax) continue;
;             const bool need_bm = kvbase + 32 * sub + 31 + 113 > qmin;
;             LAS bf16x8* qsp = qs; asm volatile("" : "+v"(qsp));
;             f32x16 s0, s1;
; #pragma unroll
;             for (int r = 0; r < 16; ++r) { s0[r] = -mref[0]; s1[r] = -mref[1]; }
;             {
;                 const LAS bf16* kp = Ks + (32 * sub + ql) * 72 + hi * 8;
;                 bf16x8 ka = *(const LAS bf16x8*)kp, kb = *(const LAS bf16x8*)(kp + 64 * 72), qa = qsp[0], qb = qsp[4 * 64];
;                 __builtin_amdgcn_sched_group_barrier(0x100, 4, 0);
; #pragma unroll
;                 for (int ks = 0; ks < 4; ++ks) { bf16x8 ka2 = ka, kb2 = kb, qa2 = qa, qb2 = qb;
;                     if (ks < 3) { ka2 = *(const LAS bf16x8*)(kp + (ks + 1) * 16); kb2 = *(const LAS bf16x8*)(kp + 64 * 72 + (ks + 1) * 16); qa2 = qsp[(ks + 1) * 64]; qb2 = qsp[(4 + ks + 1) * 64];
;                         __builtin_amdgcn_sched_group_barrier(0x100, 4, 0); }
;                     s0 = __builtin_amdgcn_mfma_f32_32x32x16_bf16(ka, qa, s0, 0, 0, 0);
;                     s1 = __builtin_amdgcn_mfma_f32_32x32x16_bf16(kb, qb, s1, 0, 0, 0);
;                     __builtin_amdgcn_sched_group_barrier(0x008, 2, 0);
;                     ka = ka2; kb = kb2; qa = qa2; qb = qb2; }
;             }
;             if (need_bm) { const LAS float* gb = tab + (159 - (q - (kvbase + 32 * sub + 4 * hi)));
; #pragma unroll
;                 for (int r = 0; r < 16; ++r) { const float bv = gb[(r & 3) + 8 * (r >> 2)]; s0[r] += bv; s1[r] += bv; } }
.LBB0_249:
	s_setprio 0
	s_lshl_b32 s38, s59, 6
	s_cmp_gt_i32 s38, s35
	v_lshlrev_b32_e32 v160, 2, v194
	s_cbranch_scc1 .LBB0_219
	v_add_u32_e32 v162, s60, v208
	v_mov_b32_e32 v163, v189
	v_add_u32_e32 v162, v162, v192
	ds_read_b128 v[164:167], v162
	ds_read_b128 v[168:171], v162 offset:9216
	ds_read_b128 v[172:175], v163
	ds_read_b128 v[182:185], v163 offset:4096
	v_sub_u32_e32 v128, v160, v178
	v_lshl_add_u32 v161, v128, 2, s50
	v_xor_b32_e32 v144, 0x80000000, v190
	v_xor_b32_e32 v128, 0x80000000, v191
	v_mov_b32_e32 v145, v144
	v_mov_b32_e32 v146, v144
	v_mov_b32_e32 v147, v144
	v_mov_b32_e32 v148, v144
	v_mov_b32_e32 v149, v144
	v_mov_b32_e32 v150, v144
	v_mov_b32_e32 v151, v144
	v_mov_b32_e32 v152, v144
	v_mov_b32_e32 v153, v144
	v_mov_b32_e32 v154, v144
	v_mov_b32_e32 v155, v144
	v_mov_b32_e32 v156, v144
	v_mov_b32_e32 v157, v144
	v_mov_b32_e32 v158, v144
	v_mov_b32_e32 v159, v144
	v_mov_b32_e32 v129, v128
	v_mov_b32_e32 v130, v128
	v_mov_b32_e32 v131, v128
	v_mov_b32_e32 v132, v128
	v_mov_b32_e32 v133, v128
	v_mov_b32_e32 v134, v128
	v_mov_b32_e32 v135, v128
	v_mov_b32_e32 v136, v128
	v_mov_b32_e32 v137, v128
	v_mov_b32_e32 v138, v128
	v_mov_b32_e32 v139, v128
	v_mov_b32_e32 v140, v128
	v_mov_b32_e32 v141, v128
	v_mov_b32_e32 v142, v128
	v_mov_b32_e32 v143, v128
	ds_read_b128 v[194:197], v162 offset:32
	ds_read_b128 v[198:201], v162 offset:9248
	ds_read_b128 v[202:205], v163 offset:1024
	ds_read_b128 v[212:215], v163 offset:5120
	s_waitcnt lgkmcnt(5)
	v_mfma_f32_32x32x16_bf16 v[144:159], v[164:167], v[172:175], v[144:159]
	s_add_i32 s46, s38, 0x90
	s_cmp_le_i32 s46, s31
	s_waitcnt lgkmcnt(4)
	v_mfma_f32_32x32x16_bf16 v[128:143], v[168:171], v[182:185], v[128:143]
	ds_read_b128 v[164:167], v162 offset:64
	ds_read_b128 v[168:171], v162 offset:9280
	ds_read_b128 v[172:175], v163 offset:2048
	ds_read_b128 v[182:185], v163 offset:6144
	s_waitcnt lgkmcnt(5)
	v_mfma_f32_32x32x16_bf16 v[144:159], v[194:197], v[202:205], v[144:159]
	s_waitcnt lgkmcnt(4)
	v_mfma_f32_32x32x16_bf16 v[128:143], v[198:201], v[212:215], v[128:143]
	ds_read_b128 v[194:197], v162 offset:96
	ds_read_b128 v[198:201], v162 offset:9312
	ds_read_b128 v[202:205], v163 offset:3072
	ds_read_b128 v[212:215], v163 offset:7168
	s_waitcnt lgkmcnt(5)
	v_mfma_f32_32x32x16_bf16 v[144:159], v[164:167], v[172:175], v[144:159]
	s_waitcnt lgkmcnt(4)
	v_mfma_f32_32x32x16_bf16 v[128:143], v[168:171], v[182:185], v[128:143]
	s_waitcnt lgkmcnt(1)
	v_mfma_f32_32x32x16_bf16 v[144:159], v[194:197], v[202:205], v[144:159]
	s_waitcnt lgkmcnt(0)
	v_mfma_f32_32x32x16_bf16 v[128:143], v[198:201], v[212:215], v[128:143]
	s_cbranch_scc1 .LBB0_252
	v_lshl_add_u32 v163, s38, 2, v161
	ds_read2_b32 v[164:165], v163 offset0:175 offset1:176
	ds_read2_b32 v[166:167], v163 offset0:177 offset1:178
	ds_read2_b32 v[168:169], v163 offset0:183 offset1:184
	ds_read2_b32 v[170:171], v163 offset0:185 offset1:186
	ds_read2_b32 v[172:173], v163 offset0:159 offset1:160
	ds_read2_b32 v[174:175], v163 offset0:161 offset1:162
	ds_read2_b32 v[182:183], v163 offset0:167 offset1:168
	ds_read2_b32 v[184:185], v163 offset0:169 offset1:170
	s_waitcnt lgkmcnt(4)
	v_pk_add_f32 v[158:159], v[158:159], v[170:171]
	v_pk_add_f32 v[156:157], v[156:157], v[168:169]
	v_pk_add_f32 v[154:155], v[154:155], v[166:167]
	v_pk_add_f32 v[152:153], v[152:153], v[164:165]
	s_waitcnt lgkmcnt(0)
	v_pk_add_f32 v[150:151], v[150:151], v[184:185]
	v_pk_add_f32 v[148:149], v[148:149], v[182:183]
	v_pk_add_f32 v[146:147], v[146:147], v[174:175]
	v_pk_add_f32 v[144:145], v[144:145], v[172:173]
	v_pk_add_f32 v[142:143], v[142:143], v[170:171]
	v_pk_add_f32 v[140:141], v[140:141], v[168:169]
	v_pk_add_f32 v[138:139], v[138:139], v[166:167]
	v_pk_add_f32 v[136:137], v[136:137], v[164:165]
	v_pk_add_f32 v[134:135], v[134:135], v[184:185]
	v_pk_add_f32 v[132:133], v[132:133], v[182:183]
	v_pk_add_f32 v[130:131], v[130:131], v[174:175]
	v_pk_add_f32 v[128:129], v[128:129], v[172:173]
